# v16 + first K-loop trip peeled with SrcC=0 on each accumulator's first MFMA; per-unit accumulator zeroing removed (in-proj A/B, uq, ukv)
# baseline (speedup 1.0000x reference)
.LBB0_267:
	s_ashr_i32 s43, s42, 31
	s_lshl_b64 s[12:13], s[42:43], 21
	s_add_u32 s48, s2, s12
	s_addc_u32 s49, s16, s13
	s_and_b64 s[12:13], s[46:47], exec
	s_cselect_b32 s21, s49, s9
	s_cselect_b32 s43, s48, s8
	s_ashr_i32 s45, s44, 31
	s_lshl_b64 s[12:13], s[44:45], 21
	s_add_u32 s50, s17, s12
	s_addc_u32 s51, s18, s13
	s_and_b64 s[12:13], s[46:47], exec
	s_cselect_b32 s45, s51, s11
	s_cselect_b32 s55, s50, s10
	s_lshl_b32 s3, s3, 8
	v_add_u32_e32 v4, s3, v171
	s_add_u32 s12, s8, 0x100080
	s_waitcnt lgkmcnt(0)
	v_ashrrev_i32_e32 v5, 31, v4
	s_addc_u32 s13, s9, 0
	v_lshl_add_u64 v[132:133], v[4:5], 2, s[6:7]
	s_add_u32 s58, s10, 0x100
	v_mov_b32_e32 v4, 0
	v_lshl_add_u64 v[134:135], s[12:13], 0, v[158:159]
	v_lshl_add_u64 v[136:137], s[12:13], 0, v[160:161]
	s_addc_u32 s59, s11, 0
	s_mov_b32 s60, -2
	s_mov_b64 s[10:11], 0
	s_branch .LpeelA

.LpeelA:
	s_add_u32 s12, s8, s10
	s_addc_u32 s13, s9, s11
	s_add_u32 s12, s12, 0x100
	s_addc_u32 s13, s13, 0
	s_add_u32 s61, s58, s10
	s_addc_u32 s62, s59, s11
	s_add_i32 s63, 0, 0x10000
	s_cmpk_eq_i32 s10, 0x1f00
	s_cselect_b32 s15, s21, s13
	s_cselect_b32 s14, s43, s12
	v_add_u32_e32 v142, s63, v169
	s_cselect_b32 s13, s45, s62
	s_cselect_b32 s12, s55, s61
	s_add_i32 s61, 0, 0x14000
	ds_read_b128 v[138:141], v142
	ds_read_b128 v[188:191], v142 offset:1024
	ds_read_b128 v[192:195], v142 offset:2048
	ds_read_b128 v[196:199], v142 offset:3072
	v_add_u32_e32 v142, s61, v169
	ds_read_b128 v[200:203], v142
	ds_read_b128 v[204:207], v142 offset:1024
	ds_read_b128 v[214:217], v142 offset:2048
	ds_read_b128 v[218:221], v142 offset:3072
	v_lshl_add_u64 v[142:143], v[134:135], 0, s[10:11]
	s_add_i32 m0, s23, 0xc000
	ds_read_b128 v[222:225], v173
	ds_read_b128 v[226:229], v173 offset:1024
	ds_read_b128 v[230:233], v173 offset:2048
	ds_read_b128 v[234:237], v173 offset:3072
	ds_read_b128 v[238:241], v173 offset:4096
	ds_read_b128 v[242:245], v173 offset:5120
	ds_read_b128 v[246:249], v173 offset:6144
	ds_read_b128 v[178:181], v173 offset:7168
	global_load_lds_dwordx4 v[142:143], off
	v_lshl_add_u64 v[142:143], v[136:137], 0, s[10:11]
	s_add_i32 m0, s23, 0xe000
	s_nop 0
	global_load_lds_dwordx4 v[142:143], off
	s_waitcnt vmcnt(8)
	s_waitcnt lgkmcnt(0)
	s_barrier
	s_setprio 1
	s_waitcnt lgkmcnt(0)
	v_mfma_f32_16x16x32_bf16 v[128:131], v[138:141], v[222:225], 0
	v_mfma_f32_16x16x32_bf16 v[124:127], v[192:195], v[222:225], 0
	v_mfma_f32_16x16x32_bf16 v[112:115], v[138:141], v[230:233], 0
	v_mfma_f32_16x16x32_bf16 v[108:111], v[192:195], v[230:233], 0
	v_mfma_f32_16x16x32_bf16 v[96:99], v[138:141], v[238:241], 0
	v_mfma_f32_16x16x32_bf16 v[92:95], v[192:195], v[238:241], 0
	v_mfma_f32_16x16x32_bf16 v[80:83], v[138:141], v[246:249], 0
	v_mfma_f32_16x16x32_bf16 v[76:79], v[192:195], v[246:249], 0
	v_mfma_f32_16x16x32_bf16 v[128:131], v[188:191], v[226:229], v[128:131]
	v_mfma_f32_16x16x32_bf16 v[124:127], v[196:199], v[226:229], v[124:127]
	v_mfma_f32_16x16x32_bf16 v[112:115], v[188:191], v[234:237], v[112:115]
	v_mfma_f32_16x16x32_bf16 v[108:111], v[196:199], v[234:237], v[108:111]
	v_mfma_f32_16x16x32_bf16 v[96:99], v[188:191], v[242:245], v[96:99]
	v_mfma_f32_16x16x32_bf16 v[92:95], v[196:199], v[242:245], v[92:95]
	v_mfma_f32_16x16x32_bf16 v[80:83], v[188:191], v[178:181], v[80:83]
	v_mfma_f32_16x16x32_bf16 v[76:79], v[196:199], v[178:181], v[76:79]
	s_setprio 0
	s_setprio 1
	v_mfma_f32_16x16x32_bf16 v[120:123], v[200:203], v[222:225], 0
	v_mfma_f32_16x16x32_bf16 v[116:119], v[214:217], v[222:225], 0
	v_mfma_f32_16x16x32_bf16 v[104:107], v[200:203], v[230:233], 0
	v_mfma_f32_16x16x32_bf16 v[100:103], v[214:217], v[230:233], 0
	v_mfma_f32_16x16x32_bf16 v[88:91], v[200:203], v[238:241], 0
	v_mfma_f32_16x16x32_bf16 v[84:87], v[214:217], v[238:241], 0
	v_mfma_f32_16x16x32_bf16 v[72:75], v[200:203], v[246:249], 0
	v_mfma_f32_16x16x32_bf16 v[68:71], v[214:217], v[246:249], 0
	v_mfma_f32_16x16x32_bf16 v[120:123], v[204:207], v[226:229], v[120:123]
	v_mfma_f32_16x16x32_bf16 v[116:119], v[218:221], v[226:229], v[116:119]
	v_mfma_f32_16x16x32_bf16 v[104:107], v[204:207], v[234:237], v[104:107]
	v_mfma_f32_16x16x32_bf16 v[100:103], v[218:221], v[234:237], v[100:103]
	v_mfma_f32_16x16x32_bf16 v[88:91], v[204:207], v[242:245], v[88:91]
	v_mfma_f32_16x16x32_bf16 v[84:87], v[218:221], v[242:245], v[84:87]
	v_mfma_f32_16x16x32_bf16 v[72:75], v[204:207], v[178:181], v[72:75]
	v_mfma_f32_16x16x32_bf16 v[68:71], v[218:221], v[178:181], v[68:71]
	s_setprio 0
	s_barrier
	s_add_i32 s62, s63, s19
	v_lshl_add_u64 v[142:143], s[12:13], 0, v[148:149]
	s_mov_b32 m0, s62
	ds_read_b128 v[178:181], v173 offset:16384
	ds_read_b128 v[222:225], v173 offset:17408
	ds_read_b128 v[226:229], v173 offset:18432
	ds_read_b128 v[230:233], v173 offset:19456
	ds_read_b128 v[234:237], v173 offset:20480
	ds_read_b128 v[238:241], v173 offset:21504
	ds_read_b128 v[242:245], v173 offset:22528
	ds_read_b128 v[246:249], v173 offset:23552
	global_load_lds_dwordx4 v[142:143], off
	s_add_i32 m0, s62, 0x2000
	s_add_u32 s62, s12, 0x100000
	v_lshl_add_u64 v[164:165], s[12:13], 0, v[144:145]
	s_addc_u32 s63, s13, 0
	s_add_i32 s61, s61, s19
	global_load_lds_dwordx4 v[164:165], off
	v_lshl_add_u64 v[250:251], s[62:63], 0, v[148:149]
	s_mov_b32 m0, s61
	v_lshl_add_u64 v[182:183], s[14:15], 0, v[146:147]
	global_load_lds_dwordx4 v[250:251], off
	v_lshl_add_u64 v[250:251], s[62:63], 0, v[144:145]
	s_add_i32 m0, s61, 0x2000
	s_nop 0
	global_load_lds_dwordx4 v[250:251], off
	v_lshl_add_u64 v[250:251], s[14:15], 0, v[150:151]
	s_mov_b32 m0, s23
	s_nop 0
	global_load_lds_dwordx4 v[250:251], off
	s_mov_b32 m0, s24
	s_nop 0
	global_load_lds_dwordx4 v[182:183], off
	s_waitcnt vmcnt(8)
	s_waitcnt lgkmcnt(0)
	s_barrier
	s_setprio 1
	s_waitcnt lgkmcnt(0)
	v_mfma_f32_16x16x32_bf16 v[64:67], v[138:141], v[178:181], 0
	v_mfma_f32_16x16x32_bf16 v[60:63], v[192:195], v[178:181], 0
	v_mfma_f32_16x16x32_bf16 v[48:51], v[138:141], v[226:229], 0
	v_mfma_f32_16x16x32_bf16 v[44:47], v[192:195], v[226:229], 0
	v_mfma_f32_16x16x32_bf16 v[32:35], v[138:141], v[234:237], 0
	v_mfma_f32_16x16x32_bf16 v[28:31], v[192:195], v[234:237], 0
	v_mfma_f32_16x16x32_bf16 v[16:19], v[138:141], v[242:245], 0
	v_mfma_f32_16x16x32_bf16 v[12:15], v[192:195], v[242:245], 0
	v_mfma_f32_16x16x32_bf16 v[64:67], v[188:191], v[222:225], v[64:67]
	v_mfma_f32_16x16x32_bf16 v[60:63], v[196:199], v[222:225], v[60:63]
	v_mfma_f32_16x16x32_bf16 v[48:51], v[188:191], v[230:233], v[48:51]
	v_mfma_f32_16x16x32_bf16 v[44:47], v[196:199], v[230:233], v[44:47]
	v_mfma_f32_16x16x32_bf16 v[32:35], v[188:191], v[238:241], v[32:35]
	v_mfma_f32_16x16x32_bf16 v[28:31], v[196:199], v[238:241], v[28:31]
	v_mfma_f32_16x16x32_bf16 v[16:19], v[188:191], v[246:249], v[16:19]
	v_mfma_f32_16x16x32_bf16 v[12:15], v[196:199], v[246:249], v[12:15]
	s_setprio 0
	s_setprio 1
	v_mfma_f32_16x16x32_bf16 v[56:59], v[200:203], v[178:181], 0
	v_mfma_f32_16x16x32_bf16 v[52:55], v[214:217], v[178:181], 0
	v_mfma_f32_16x16x32_bf16 v[40:43], v[200:203], v[226:229], 0
	v_mfma_f32_16x16x32_bf16 v[36:39], v[214:217], v[226:229], 0
	v_mfma_f32_16x16x32_bf16 v[24:27], v[200:203], v[234:237], 0
	v_mfma_f32_16x16x32_bf16 v[20:23], v[214:217], v[234:237], 0
	v_mfma_f32_16x16x32_bf16 v[8:11], v[200:203], v[242:245], 0
	v_mfma_f32_16x16x32_bf16 v[4:7], v[214:217], v[242:245], 0
	v_mfma_f32_16x16x32_bf16 v[56:59], v[204:207], v[222:225], v[56:59]
	v_mfma_f32_16x16x32_bf16 v[52:55], v[218:221], v[222:225], v[52:55]
	v_mfma_f32_16x16x32_bf16 v[40:43], v[204:207], v[230:233], v[40:43]
	v_mfma_f32_16x16x32_bf16 v[36:39], v[218:221], v[230:233], v[36:39]
	v_mfma_f32_16x16x32_bf16 v[24:27], v[204:207], v[238:241], v[24:27]
	v_mfma_f32_16x16x32_bf16 v[20:23], v[218:221], v[238:241], v[20:23]
	v_mfma_f32_16x16x32_bf16 v[8:11], v[204:207], v[246:249], v[8:11]
	v_mfma_f32_16x16x32_bf16 v[4:7], v[218:221], v[246:249], v[4:7]
	s_setprio 0
	s_barrier
	s_add_i32 s61, 0, 0x18000
	v_add_u32_e32 v162, s61, v169
	s_add_i32 s62, 0, 0x1c000
	ds_read_b128 v[138:141], v162
	ds_read_b128 v[178:181], v162 offset:1024
	ds_read_b128 v[188:191], v162 offset:2048
	ds_read_b128 v[192:195], v162 offset:3072
	v_add_u32_e32 v162, s62, v169
	ds_read_b128 v[196:199], v162
	ds_read_b128 v[200:203], v162 offset:1024
	ds_read_b128 v[204:207], v162 offset:2048
	ds_read_b128 v[214:217], v162 offset:3072
	s_add_u32 s14, s14, 0x100000
	s_addc_u32 s15, s15, 0
	s_mov_b32 m0, s25
	v_lshl_add_u64 v[184:185], s[14:15], 0, v[150:151]
	ds_read_b128 v[218:221], v173 offset:32768
	ds_read_b128 v[222:225], v173 offset:33792
	ds_read_b128 v[226:229], v173 offset:34816
	ds_read_b128 v[230:233], v173 offset:35840
	ds_read_b128 v[234:237], v173 offset:36864
	ds_read_b128 v[238:241], v173 offset:37888
	ds_read_b128 v[242:245], v173 offset:38912
	ds_read_b128 v[246:249], v173 offset:39936
	global_load_lds_dwordx4 v[184:185], off
	v_lshl_add_u64 v[184:185], s[14:15], 0, v[146:147]
	s_mov_b32 m0, s30
	s_nop 0
	global_load_lds_dwordx4 v[184:185], off
	s_waitcnt vmcnt(8)
	s_waitcnt lgkmcnt(0)
	s_barrier
	s_setprio 1
	s_waitcnt lgkmcnt(0)
	v_mfma_f32_16x16x32_bf16 v[128:131], v[138:141], v[218:221], v[128:131]
	v_mfma_f32_16x16x32_bf16 v[124:127], v[188:191], v[218:221], v[124:127]
	v_mfma_f32_16x16x32_bf16 v[112:115], v[138:141], v[226:229], v[112:115]
	v_mfma_f32_16x16x32_bf16 v[108:111], v[188:191], v[226:229], v[108:111]
	v_mfma_f32_16x16x32_bf16 v[96:99], v[138:141], v[234:237], v[96:99]
	v_mfma_f32_16x16x32_bf16 v[92:95], v[188:191], v[234:237], v[92:95]
	v_mfma_f32_16x16x32_bf16 v[80:83], v[138:141], v[242:245], v[80:83]
	v_mfma_f32_16x16x32_bf16 v[76:79], v[188:191], v[242:245], v[76:79]
	v_mfma_f32_16x16x32_bf16 v[128:131], v[178:181], v[222:225], v[128:131]
	v_mfma_f32_16x16x32_bf16 v[124:127], v[192:195], v[222:225], v[124:127]
	v_mfma_f32_16x16x32_bf16 v[112:115], v[178:181], v[230:233], v[112:115]
	v_mfma_f32_16x16x32_bf16 v[108:111], v[192:195], v[230:233], v[108:111]
	v_mfma_f32_16x16x32_bf16 v[96:99], v[178:181], v[238:241], v[96:99]
	v_mfma_f32_16x16x32_bf16 v[92:95], v[192:195], v[238:241], v[92:95]
	v_mfma_f32_16x16x32_bf16 v[80:83], v[178:181], v[246:249], v[80:83]
	v_mfma_f32_16x16x32_bf16 v[76:79], v[192:195], v[246:249], v[76:79]
	s_setprio 0
	s_setprio 1
	v_mfma_f32_16x16x32_bf16 v[120:123], v[196:199], v[218:221], v[120:123]
	v_mfma_f32_16x16x32_bf16 v[116:119], v[204:207], v[218:221], v[116:119]
	v_mfma_f32_16x16x32_bf16 v[104:107], v[196:199], v[226:229], v[104:107]
	v_mfma_f32_16x16x32_bf16 v[100:103], v[204:207], v[226:229], v[100:103]
	v_mfma_f32_16x16x32_bf16 v[88:91], v[196:199], v[234:237], v[88:91]
	v_mfma_f32_16x16x32_bf16 v[84:87], v[204:207], v[234:237], v[84:87]
	v_mfma_f32_16x16x32_bf16 v[72:75], v[196:199], v[242:245], v[72:75]
	v_mfma_f32_16x16x32_bf16 v[68:71], v[204:207], v[242:245], v[68:71]
	v_mfma_f32_16x16x32_bf16 v[120:123], v[200:203], v[222:225], v[120:123]
	v_mfma_f32_16x16x32_bf16 v[116:119], v[214:217], v[222:225], v[116:119]
	v_mfma_f32_16x16x32_bf16 v[104:107], v[200:203], v[230:233], v[104:107]
	v_mfma_f32_16x16x32_bf16 v[100:103], v[214:217], v[230:233], v[100:103]
	v_mfma_f32_16x16x32_bf16 v[88:91], v[200:203], v[238:241], v[88:91]
	v_mfma_f32_16x16x32_bf16 v[84:87], v[214:217], v[238:241], v[84:87]
	v_mfma_f32_16x16x32_bf16 v[72:75], v[200:203], v[246:249], v[72:75]
	v_mfma_f32_16x16x32_bf16 v[68:71], v[214:217], v[246:249], v[68:71]
	s_setprio 0
	s_barrier
	s_add_i32 s14, s61, s19
	v_lshl_add_u64 v[142:143], v[142:143], 0, s[34:35]
	s_mov_b32 m0, s14
	ds_read_b128 v[218:221], v173 offset:49152
	ds_read_b128 v[222:225], v173 offset:50176
	ds_read_b128 v[226:229], v173 offset:51200
	ds_read_b128 v[230:233], v173 offset:52224
	ds_read_b128 v[234:237], v173 offset:53248
	ds_read_b128 v[238:241], v173 offset:54272
	ds_read_b128 v[242:245], v173 offset:55296
	ds_read_b128 v[246:249], v173 offset:56320
	global_load_lds_dwordx4 v[142:143], off
	s_add_i32 m0, s14, 0x2000
	s_add_u32 s12, s12, 0x100080
	v_lshl_add_u64 v[142:143], v[164:165], 0, s[34:35]
	s_addc_u32 s13, s13, 0
	s_add_i32 s14, s62, s19
	global_load_lds_dwordx4 v[142:143], off
	v_lshl_add_u64 v[142:143], s[12:13], 0, v[148:149]
	s_mov_b32 m0, s14
	s_nop 0
	global_load_lds_dwordx4 v[142:143], off
	v_lshl_add_u64 v[142:143], s[12:13], 0, v[144:145]
	s_add_i32 m0, s14, 0x2000
	s_nop 0
	global_load_lds_dwordx4 v[142:143], off
	v_lshl_add_u64 v[142:143], v[250:251], 0, s[34:35]
	s_mov_b32 m0, s33
	s_nop 0
	global_load_lds_dwordx4 v[142:143], off
	v_lshl_add_u64 v[142:143], v[182:183], 0, s[34:35]
	s_mov_b32 m0, s52
	s_nop 0
	global_load_lds_dwordx4 v[142:143], off
	s_waitcnt vmcnt(8)
	s_waitcnt lgkmcnt(0)
	s_barrier
	s_setprio 1
	s_waitcnt lgkmcnt(0)
	v_mfma_f32_16x16x32_bf16 v[64:67], v[138:141], v[218:221], v[64:67]
	v_mfma_f32_16x16x32_bf16 v[60:63], v[188:191], v[218:221], v[60:63]
	v_mfma_f32_16x16x32_bf16 v[48:51], v[138:141], v[226:229], v[48:51]
	v_mfma_f32_16x16x32_bf16 v[44:47], v[188:191], v[226:229], v[44:47]
	v_mfma_f32_16x16x32_bf16 v[32:35], v[138:141], v[234:237], v[32:35]
	v_mfma_f32_16x16x32_bf16 v[28:31], v[188:191], v[234:237], v[28:31]
	v_mfma_f32_16x16x32_bf16 v[16:19], v[138:141], v[242:245], v[16:19]
	v_mfma_f32_16x16x32_bf16 v[12:15], v[188:191], v[242:245], v[12:15]
	v_mfma_f32_16x16x32_bf16 v[64:67], v[178:181], v[222:225], v[64:67]
	v_mfma_f32_16x16x32_bf16 v[60:63], v[192:195], v[222:225], v[60:63]
	v_mfma_f32_16x16x32_bf16 v[48:51], v[178:181], v[230:233], v[48:51]
	v_mfma_f32_16x16x32_bf16 v[44:47], v[192:195], v[230:233], v[44:47]
	v_mfma_f32_16x16x32_bf16 v[32:35], v[178:181], v[238:241], v[32:35]
	v_mfma_f32_16x16x32_bf16 v[28:31], v[192:195], v[238:241], v[28:31]
	v_mfma_f32_16x16x32_bf16 v[16:19], v[178:181], v[246:249], v[16:19]
	v_mfma_f32_16x16x32_bf16 v[12:15], v[192:195], v[246:249], v[12:15]
	s_setprio 0
	s_setprio 1
	v_mfma_f32_16x16x32_bf16 v[56:59], v[196:199], v[218:221], v[56:59]
	v_mfma_f32_16x16x32_bf16 v[52:55], v[204:207], v[218:221], v[52:55]
	v_mfma_f32_16x16x32_bf16 v[40:43], v[196:199], v[226:229], v[40:43]
	v_mfma_f32_16x16x32_bf16 v[36:39], v[204:207], v[226:229], v[36:39]
	v_mfma_f32_16x16x32_bf16 v[24:27], v[196:199], v[234:237], v[24:27]
	v_mfma_f32_16x16x32_bf16 v[20:23], v[204:207], v[234:237], v[20:23]
	v_mfma_f32_16x16x32_bf16 v[8:11], v[196:199], v[242:245], v[8:11]
	v_mfma_f32_16x16x32_bf16 v[4:7], v[204:207], v[242:245], v[4:7]
	v_mfma_f32_16x16x32_bf16 v[56:59], v[200:203], v[222:225], v[56:59]
	v_mfma_f32_16x16x32_bf16 v[52:55], v[214:217], v[222:225], v[52:55]
	v_mfma_f32_16x16x32_bf16 v[40:43], v[200:203], v[230:233], v[40:43]
	v_mfma_f32_16x16x32_bf16 v[36:39], v[214:217], v[230:233], v[36:39]
	v_mfma_f32_16x16x32_bf16 v[24:27], v[200:203], v[238:241], v[24:27]
	v_mfma_f32_16x16x32_bf16 v[20:23], v[214:217], v[238:241], v[20:23]
	v_mfma_f32_16x16x32_bf16 v[8:11], v[200:203], v[246:249], v[8:11]
	v_mfma_f32_16x16x32_bf16 v[4:7], v[214:217], v[246:249], v[4:7]
	s_setprio 0
	s_barrier
	s_add_i32 s60, s60, 2
	s_add_u32 s10, s10, 0x100
	s_addc_u32 s11, s11, 0
	s_cmp_gt_u32 s60, 61
	s_cbranch_scc1 .LBB0_271
	s_branch .LBB0_269

.LBB0_375:
	s_ashr_i32 s51, s50, 31
	s_lshl_b64 s[14:15], s[50:51], 21
	s_add_u32 s58, s2, s14
	s_addc_u32 s59, s16, s15
	s_and_b64 s[14:15], s[54:55], exec
	s_cselect_b32 s21, s59, s9
	s_cselect_b32 s51, s58, s8
	s_ashr_i32 s53, s52, 31
	s_lshl_b64 s[14:15], s[52:53], 21
	s_add_u32 s60, s17, s14
	s_addc_u32 s61, s18, s15
	s_and_b64 s[14:15], s[54:55], exec
	s_cselect_b32 s53, s61, s13
	s_cselect_b32 s67, s60, s12
	s_lshl_b32 s3, s10, 8
	s_waitcnt lgkmcnt(0)
	v_add_u32_e32 v4, s3, v169
	s_add_u32 s10, s8, 0x100080
	v_ashrrev_i32_e32 v5, 31, v4
	s_addc_u32 s11, s9, 0
	v_lshl_add_u64 v[132:133], v[4:5], 2, s[44:45]
	s_add_u32 s68, s12, 0x100
	v_mov_b32_e32 v4, 0
	v_lshl_add_u64 v[134:135], s[10:11], 0, v[158:159]
	v_lshl_add_u64 v[136:137], s[10:11], 0, v[160:161]
	s_addc_u32 s69, s13, 0
	s_mov_b32 s70, -2
	s_mov_b64 s[10:11], 0
	s_branch .LpeelB

.LpeelB:
	s_add_u32 s12, s8, s10
	s_addc_u32 s13, s9, s11
	s_add_u32 s12, s12, 0x100
	s_addc_u32 s13, s13, 0
	s_add_u32 s71, s68, s10
	s_addc_u32 s72, s69, s11
	s_add_i32 s73, 0, 0x10000
	s_cmpk_eq_i32 s10, 0x1f00
	s_cselect_b32 s15, s21, s13
	s_cselect_b32 s14, s51, s12
	v_add_u32_e32 v2, s73, v167
	s_cselect_b32 s13, s53, s72
	s_cselect_b32 s12, s67, s71
	s_add_i32 s71, 0, 0x14000
	ds_read_b128 v[138:141], v2
	ds_read_b128 v[176:179], v2 offset:1024
	ds_read_b128 v[188:191], v2 offset:2048
	ds_read_b128 v[192:195], v2 offset:3072
	v_add_u32_e32 v2, s71, v167
	ds_read_b128 v[196:199], v2
	ds_read_b128 v[200:203], v2 offset:1024
	ds_read_b128 v[204:207], v2 offset:2048
	ds_read_b128 v[214:217], v2 offset:3072
	v_lshl_add_u64 v[142:143], v[134:135], 0, s[10:11]
	s_add_i32 m0, s23, 0xc000
	ds_read_b128 v[218:221], v171
	ds_read_b128 v[222:225], v171 offset:1024
	ds_read_b128 v[226:229], v171 offset:2048
	ds_read_b128 v[230:233], v171 offset:3072
	ds_read_b128 v[234:237], v171 offset:4096
	ds_read_b128 v[238:241], v171 offset:5120
	ds_read_b128 v[242:245], v171 offset:6144
	ds_read_b128 v[246:249], v171 offset:7168
	global_load_lds_dwordx4 v[142:143], off
	v_lshl_add_u64 v[142:143], v[136:137], 0, s[10:11]
	s_add_i32 m0, s23, 0xe000
	s_nop 0
	global_load_lds_dwordx4 v[142:143], off
	s_waitcnt vmcnt(8)
	s_waitcnt lgkmcnt(0)
	s_barrier
	s_setprio 1
	s_waitcnt lgkmcnt(0)
	v_mfma_f32_16x16x32_bf16 v[128:131], v[138:141], v[218:221], 0
	v_mfma_f32_16x16x32_bf16 v[124:127], v[188:191], v[218:221], 0
	v_mfma_f32_16x16x32_bf16 v[112:115], v[138:141], v[226:229], 0
	v_mfma_f32_16x16x32_bf16 v[108:111], v[188:191], v[226:229], 0
	v_mfma_f32_16x16x32_bf16 v[96:99], v[138:141], v[234:237], 0
	v_mfma_f32_16x16x32_bf16 v[92:95], v[188:191], v[234:237], 0
	v_mfma_f32_16x16x32_bf16 v[80:83], v[138:141], v[242:245], 0
	v_mfma_f32_16x16x32_bf16 v[76:79], v[188:191], v[242:245], 0
	v_mfma_f32_16x16x32_bf16 v[128:131], v[176:179], v[222:225], v[128:131]
	v_mfma_f32_16x16x32_bf16 v[124:127], v[192:195], v[222:225], v[124:127]
	v_mfma_f32_16x16x32_bf16 v[112:115], v[176:179], v[230:233], v[112:115]
	v_mfma_f32_16x16x32_bf16 v[108:111], v[192:195], v[230:233], v[108:111]
	v_mfma_f32_16x16x32_bf16 v[96:99], v[176:179], v[238:241], v[96:99]
	v_mfma_f32_16x16x32_bf16 v[92:95], v[192:195], v[238:241], v[92:95]
	v_mfma_f32_16x16x32_bf16 v[80:83], v[176:179], v[246:249], v[80:83]
	v_mfma_f32_16x16x32_bf16 v[76:79], v[192:195], v[246:249], v[76:79]
	s_setprio 0
	s_setprio 1
	v_mfma_f32_16x16x32_bf16 v[120:123], v[196:199], v[218:221], 0
	v_mfma_f32_16x16x32_bf16 v[116:119], v[204:207], v[218:221], 0
	v_mfma_f32_16x16x32_bf16 v[104:107], v[196:199], v[226:229], 0
	v_mfma_f32_16x16x32_bf16 v[100:103], v[204:207], v[226:229], 0
	v_mfma_f32_16x16x32_bf16 v[88:91], v[196:199], v[234:237], 0
	v_mfma_f32_16x16x32_bf16 v[84:87], v[204:207], v[234:237], 0
	v_mfma_f32_16x16x32_bf16 v[72:75], v[196:199], v[242:245], 0
	v_mfma_f32_16x16x32_bf16 v[68:71], v[204:207], v[242:245], 0
	v_mfma_f32_16x16x32_bf16 v[120:123], v[200:203], v[222:225], v[120:123]
	v_mfma_f32_16x16x32_bf16 v[116:119], v[214:217], v[222:225], v[116:119]
	v_mfma_f32_16x16x32_bf16 v[104:107], v[200:203], v[230:233], v[104:107]
	v_mfma_f32_16x16x32_bf16 v[100:103], v[214:217], v[230:233], v[100:103]
	v_mfma_f32_16x16x32_bf16 v[88:91], v[200:203], v[238:241], v[88:91]
	v_mfma_f32_16x16x32_bf16 v[84:87], v[214:217], v[238:241], v[84:87]
	v_mfma_f32_16x16x32_bf16 v[72:75], v[200:203], v[246:249], v[72:75]
	v_mfma_f32_16x16x32_bf16 v[68:71], v[214:217], v[246:249], v[68:71]
	s_setprio 0
	s_barrier
	s_add_i32 s72, s73, s19
	v_lshl_add_u64 v[142:143], s[12:13], 0, v[146:147]
	s_mov_b32 m0, s72
	ds_read_b128 v[218:221], v171 offset:16384
	ds_read_b128 v[222:225], v171 offset:17408
	ds_read_b128 v[226:229], v171 offset:18432
	ds_read_b128 v[230:233], v171 offset:19456
	ds_read_b128 v[234:237], v171 offset:20480
	ds_read_b128 v[238:241], v171 offset:21504
	ds_read_b128 v[242:245], v171 offset:22528
	ds_read_b128 v[246:249], v171 offset:23552
	global_load_lds_dwordx4 v[142:143], off
	s_add_i32 m0, s72, 0x2000
	s_add_u32 s72, s12, 0x100000
	v_lshl_add_u64 v[164:165], s[12:13], 0, v[150:151]
	s_addc_u32 s73, s13, 0
	s_add_i32 s71, s71, s19
	global_load_lds_dwordx4 v[164:165], off
	v_lshl_add_u64 v[180:181], s[72:73], 0, v[146:147]
	s_mov_b32 m0, s71
	v_lshl_add_u64 v[182:183], s[14:15], 0, v[148:149]
	global_load_lds_dwordx4 v[180:181], off
	v_lshl_add_u64 v[180:181], s[72:73], 0, v[150:151]
	s_add_i32 m0, s71, 0x2000
	s_nop 0
	global_load_lds_dwordx4 v[180:181], off
	v_lshl_add_u64 v[180:181], s[14:15], 0, v[144:145]
	s_mov_b32 m0, s23
	s_nop 0
	global_load_lds_dwordx4 v[180:181], off
	s_mov_b32 m0, s24
	s_nop 0
	global_load_lds_dwordx4 v[182:183], off
	s_waitcnt vmcnt(8)
	s_waitcnt lgkmcnt(0)
	s_barrier
	s_setprio 1
	s_waitcnt lgkmcnt(0)
	v_mfma_f32_16x16x32_bf16 v[64:67], v[138:141], v[218:221], 0
	v_mfma_f32_16x16x32_bf16 v[60:63], v[188:191], v[218:221], 0
	v_mfma_f32_16x16x32_bf16 v[48:51], v[138:141], v[226:229], 0
	v_mfma_f32_16x16x32_bf16 v[44:47], v[188:191], v[226:229], 0
	v_mfma_f32_16x16x32_bf16 v[32:35], v[138:141], v[234:237], 0
	v_mfma_f32_16x16x32_bf16 v[28:31], v[188:191], v[234:237], 0
	v_mfma_f32_16x16x32_bf16 v[16:19], v[138:141], v[242:245], 0
	v_mfma_f32_16x16x32_bf16 v[12:15], v[188:191], v[242:245], 0
	v_mfma_f32_16x16x32_bf16 v[64:67], v[176:179], v[222:225], v[64:67]
	v_mfma_f32_16x16x32_bf16 v[60:63], v[192:195], v[222:225], v[60:63]
	v_mfma_f32_16x16x32_bf16 v[48:51], v[176:179], v[230:233], v[48:51]
	v_mfma_f32_16x16x32_bf16 v[44:47], v[192:195], v[230:233], v[44:47]
	v_mfma_f32_16x16x32_bf16 v[32:35], v[176:179], v[238:241], v[32:35]
	v_mfma_f32_16x16x32_bf16 v[28:31], v[192:195], v[238:241], v[28:31]
	v_mfma_f32_16x16x32_bf16 v[16:19], v[176:179], v[246:249], v[16:19]
	v_mfma_f32_16x16x32_bf16 v[12:15], v[192:195], v[246:249], v[12:15]
	s_setprio 0
	s_setprio 1
	v_mfma_f32_16x16x32_bf16 v[56:59], v[196:199], v[218:221], 0
	v_mfma_f32_16x16x32_bf16 v[52:55], v[204:207], v[218:221], 0
	v_mfma_f32_16x16x32_bf16 v[40:43], v[196:199], v[226:229], 0
	v_mfma_f32_16x16x32_bf16 v[36:39], v[204:207], v[226:229], 0
	v_mfma_f32_16x16x32_bf16 v[24:27], v[196:199], v[234:237], 0
	v_mfma_f32_16x16x32_bf16 v[20:23], v[204:207], v[234:237], 0
	v_mfma_f32_16x16x32_bf16 v[8:11], v[196:199], v[242:245], 0
	v_mfma_f32_16x16x32_bf16 v[4:7], v[204:207], v[242:245], 0
	v_mfma_f32_16x16x32_bf16 v[56:59], v[200:203], v[222:225], v[56:59]
	v_mfma_f32_16x16x32_bf16 v[52:55], v[214:217], v[222:225], v[52:55]
	v_mfma_f32_16x16x32_bf16 v[40:43], v[200:203], v[230:233], v[40:43]
	v_mfma_f32_16x16x32_bf16 v[36:39], v[214:217], v[230:233], v[36:39]
	v_mfma_f32_16x16x32_bf16 v[24:27], v[200:203], v[238:241], v[24:27]
	v_mfma_f32_16x16x32_bf16 v[20:23], v[214:217], v[238:241], v[20:23]
	v_mfma_f32_16x16x32_bf16 v[8:11], v[200:203], v[246:249], v[8:11]
	v_mfma_f32_16x16x32_bf16 v[4:7], v[214:217], v[246:249], v[4:7]
	s_setprio 0
	s_barrier
	s_add_i32 s71, 0, 0x18000
	v_add_u32_e32 v2, s71, v167
	s_add_i32 s72, 0, 0x1c000
	ds_read_b128 v[138:141], v2
	ds_read_b128 v[176:179], v2 offset:1024
	ds_read_b128 v[188:191], v2 offset:2048
	ds_read_b128 v[192:195], v2 offset:3072
	v_add_u32_e32 v2, s72, v167
	ds_read_b128 v[196:199], v2
	ds_read_b128 v[200:203], v2 offset:1024
	ds_read_b128 v[204:207], v2 offset:2048
	ds_read_b128 v[214:217], v2 offset:3072
	s_add_u32 s14, s14, 0x100000
	s_addc_u32 s15, s15, 0
	s_mov_b32 m0, s25
	v_lshl_add_u64 v[184:185], s[14:15], 0, v[144:145]
	ds_read_b128 v[218:221], v171 offset:32768
	ds_read_b128 v[222:225], v171 offset:33792
	ds_read_b128 v[226:229], v171 offset:34816
	ds_read_b128 v[230:233], v171 offset:35840
	ds_read_b128 v[234:237], v171 offset:36864
	ds_read_b128 v[238:241], v171 offset:37888
	ds_read_b128 v[242:245], v171 offset:38912
	ds_read_b128 v[246:249], v171 offset:39936
	global_load_lds_dwordx4 v[184:185], off
	v_lshl_add_u64 v[184:185], s[14:15], 0, v[148:149]
	s_mov_b32 m0, s30
	s_nop 0
	global_load_lds_dwordx4 v[184:185], off
	s_waitcnt vmcnt(8)
	s_waitcnt lgkmcnt(0)
	s_barrier
	s_setprio 1
	s_waitcnt lgkmcnt(0)
	v_mfma_f32_16x16x32_bf16 v[128:131], v[138:141], v[218:221], v[128:131]
	v_mfma_f32_16x16x32_bf16 v[124:127], v[188:191], v[218:221], v[124:127]
	v_mfma_f32_16x16x32_bf16 v[112:115], v[138:141], v[226:229], v[112:115]
	v_mfma_f32_16x16x32_bf16 v[108:111], v[188:191], v[226:229], v[108:111]
	v_mfma_f32_16x16x32_bf16 v[96:99], v[138:141], v[234:237], v[96:99]
	v_mfma_f32_16x16x32_bf16 v[92:95], v[188:191], v[234:237], v[92:95]
	v_mfma_f32_16x16x32_bf16 v[80:83], v[138:141], v[242:245], v[80:83]
	v_mfma_f32_16x16x32_bf16 v[76:79], v[188:191], v[242:245], v[76:79]
	v_mfma_f32_16x16x32_bf16 v[128:131], v[176:179], v[222:225], v[128:131]
	v_mfma_f32_16x16x32_bf16 v[124:127], v[192:195], v[222:225], v[124:127]
	v_mfma_f32_16x16x32_bf16 v[112:115], v[176:179], v[230:233], v[112:115]
	v_mfma_f32_16x16x32_bf16 v[108:111], v[192:195], v[230:233], v[108:111]
	v_mfma_f32_16x16x32_bf16 v[96:99], v[176:179], v[238:241], v[96:99]
	v_mfma_f32_16x16x32_bf16 v[92:95], v[192:195], v[238:241], v[92:95]
	v_mfma_f32_16x16x32_bf16 v[80:83], v[176:179], v[246:249], v[80:83]
	v_mfma_f32_16x16x32_bf16 v[76:79], v[192:195], v[246:249], v[76:79]
	s_setprio 0
	s_setprio 1
	v_mfma_f32_16x16x32_bf16 v[120:123], v[196:199], v[218:221], v[120:123]
	v_mfma_f32_16x16x32_bf16 v[116:119], v[204:207], v[218:221], v[116:119]
	v_mfma_f32_16x16x32_bf16 v[104:107], v[196:199], v[226:229], v[104:107]
	v_mfma_f32_16x16x32_bf16 v[100:103], v[204:207], v[226:229], v[100:103]
	v_mfma_f32_16x16x32_bf16 v[88:91], v[196:199], v[234:237], v[88:91]
	v_mfma_f32_16x16x32_bf16 v[84:87], v[204:207], v[234:237], v[84:87]
	v_mfma_f32_16x16x32_bf16 v[72:75], v[196:199], v[242:245], v[72:75]
	v_mfma_f32_16x16x32_bf16 v[68:71], v[204:207], v[242:245], v[68:71]
	v_mfma_f32_16x16x32_bf16 v[120:123], v[200:203], v[222:225], v[120:123]
	v_mfma_f32_16x16x32_bf16 v[116:119], v[214:217], v[222:225], v[116:119]
	v_mfma_f32_16x16x32_bf16 v[104:107], v[200:203], v[230:233], v[104:107]
	v_mfma_f32_16x16x32_bf16 v[100:103], v[214:217], v[230:233], v[100:103]
	v_mfma_f32_16x16x32_bf16 v[88:91], v[200:203], v[238:241], v[88:91]
	v_mfma_f32_16x16x32_bf16 v[84:87], v[214:217], v[238:241], v[84:87]
	v_mfma_f32_16x16x32_bf16 v[72:75], v[200:203], v[246:249], v[72:75]
	v_mfma_f32_16x16x32_bf16 v[68:71], v[214:217], v[246:249], v[68:71]
	s_setprio 0
	s_barrier
	s_add_i32 s14, s71, s19
	v_lshl_add_u64 v[142:143], v[142:143], 0, s[34:35]
	s_mov_b32 m0, s14
	ds_read_b128 v[218:221], v171 offset:49152
	ds_read_b128 v[222:225], v171 offset:50176
	ds_read_b128 v[226:229], v171 offset:51200
	ds_read_b128 v[230:233], v171 offset:52224
	ds_read_b128 v[234:237], v171 offset:53248
	ds_read_b128 v[238:241], v171 offset:54272
	ds_read_b128 v[242:245], v171 offset:55296
	ds_read_b128 v[246:249], v171 offset:56320
	global_load_lds_dwordx4 v[142:143], off
	s_add_i32 m0, s14, 0x2000
	s_add_u32 s12, s12, 0x100080
	v_lshl_add_u64 v[142:143], v[164:165], 0, s[34:35]
	s_addc_u32 s13, s13, 0
	s_add_i32 s14, s72, s19
	global_load_lds_dwordx4 v[142:143], off
	v_lshl_add_u64 v[142:143], s[12:13], 0, v[146:147]
	s_mov_b32 m0, s14
	s_nop 0
	global_load_lds_dwordx4 v[142:143], off
	v_lshl_add_u64 v[142:143], s[12:13], 0, v[150:151]
	s_add_i32 m0, s14, 0x2000
	s_nop 0
	global_load_lds_dwordx4 v[142:143], off
	v_lshl_add_u64 v[142:143], v[180:181], 0, s[34:35]
	s_mov_b32 m0, s64
	s_nop 0
	global_load_lds_dwordx4 v[142:143], off
	v_lshl_add_u64 v[142:143], v[182:183], 0, s[34:35]
	s_mov_b32 m0, s65
	s_nop 0
	global_load_lds_dwordx4 v[142:143], off
	s_waitcnt vmcnt(8)
	s_waitcnt lgkmcnt(0)
	s_barrier
	s_setprio 1
	s_waitcnt lgkmcnt(0)
	v_mfma_f32_16x16x32_bf16 v[64:67], v[138:141], v[218:221], v[64:67]
	v_mfma_f32_16x16x32_bf16 v[60:63], v[188:191], v[218:221], v[60:63]
	v_mfma_f32_16x16x32_bf16 v[48:51], v[138:141], v[226:229], v[48:51]
	v_mfma_f32_16x16x32_bf16 v[44:47], v[188:191], v[226:229], v[44:47]
	v_mfma_f32_16x16x32_bf16 v[32:35], v[138:141], v[234:237], v[32:35]
	v_mfma_f32_16x16x32_bf16 v[28:31], v[188:191], v[234:237], v[28:31]
	v_mfma_f32_16x16x32_bf16 v[16:19], v[138:141], v[242:245], v[16:19]
	v_mfma_f32_16x16x32_bf16 v[12:15], v[188:191], v[242:245], v[12:15]
	v_mfma_f32_16x16x32_bf16 v[64:67], v[176:179], v[222:225], v[64:67]
	v_mfma_f32_16x16x32_bf16 v[60:63], v[192:195], v[222:225], v[60:63]
	v_mfma_f32_16x16x32_bf16 v[48:51], v[176:179], v[230:233], v[48:51]
	v_mfma_f32_16x16x32_bf16 v[44:47], v[192:195], v[230:233], v[44:47]
	v_mfma_f32_16x16x32_bf16 v[32:35], v[176:179], v[238:241], v[32:35]
	v_mfma_f32_16x16x32_bf16 v[28:31], v[192:195], v[238:241], v[28:31]
	v_mfma_f32_16x16x32_bf16 v[16:19], v[176:179], v[246:249], v[16:19]
	v_mfma_f32_16x16x32_bf16 v[12:15], v[192:195], v[246:249], v[12:15]
	s_setprio 0
	s_setprio 1
	v_mfma_f32_16x16x32_bf16 v[56:59], v[196:199], v[218:221], v[56:59]
	v_mfma_f32_16x16x32_bf16 v[52:55], v[204:207], v[218:221], v[52:55]
	v_mfma_f32_16x16x32_bf16 v[40:43], v[196:199], v[226:229], v[40:43]
	v_mfma_f32_16x16x32_bf16 v[36:39], v[204:207], v[226:229], v[36:39]
	v_mfma_f32_16x16x32_bf16 v[24:27], v[196:199], v[234:237], v[24:27]
	v_mfma_f32_16x16x32_bf16 v[20:23], v[204:207], v[234:237], v[20:23]
	v_mfma_f32_16x16x32_bf16 v[8:11], v[196:199], v[242:245], v[8:11]
	v_mfma_f32_16x16x32_bf16 v[4:7], v[204:207], v[242:245], v[4:7]
	v_mfma_f32_16x16x32_bf16 v[56:59], v[200:203], v[222:225], v[56:59]
	v_mfma_f32_16x16x32_bf16 v[52:55], v[214:217], v[222:225], v[52:55]
	v_mfma_f32_16x16x32_bf16 v[40:43], v[200:203], v[230:233], v[40:43]
	v_mfma_f32_16x16x32_bf16 v[36:39], v[214:217], v[230:233], v[36:39]
	v_mfma_f32_16x16x32_bf16 v[24:27], v[200:203], v[238:241], v[24:27]
	v_mfma_f32_16x16x32_bf16 v[20:23], v[214:217], v[238:241], v[20:23]
	v_mfma_f32_16x16x32_bf16 v[8:11], v[200:203], v[246:249], v[8:11]
	v_mfma_f32_16x16x32_bf16 v[4:7], v[214:217], v[246:249], v[4:7]
	s_setprio 0
	s_barrier
	s_add_i32 s70, s70, 2
	s_add_u32 s10, s10, 0x100
	s_addc_u32 s11, s11, 0
	s_cmp_gt_u32 s70, 61
	s_cbranch_scc1 .LBB0_379
	s_branch .LBB0_377

.LBB0_437:
	s_ashr_i32 s47, s46, 31
	s_lshl_b64 s[0:1], s[46:47], 19
	s_add_u32 s48, s16, s0
	s_addc_u32 s49, s17, s1
	s_and_b64 s[0:1], s[36:37], exec
	s_cselect_b32 s3, s49, s9
	s_cselect_b32 s21, s48, s8
	s_ashr_i32 s45, s44, 31
	s_lshl_b64 s[0:1], s[44:45], 19
	s_add_u32 s50, s2, s0
	s_addc_u32 s51, s14, s1
	s_and_b64 s[0:1], s[36:37], exec
	s_cselect_b32 s47, s51, s11
	s_cselect_b32 s53, s50, s10
	s_lshl_b32 s45, s12, 8
	v_add_u32_e32 v4, s45, v189
	v_ashrrev_i32_e32 v5, 31, v4
	v_lshlrev_b64 v[6:7], 6, v[4:5]
	v_or_b32_e32 v4, 16, v4
	v_ashrrev_i32_e32 v5, 31, v4
	s_add_u32 s0, s8, 0x40080
	v_lshlrev_b64 v[4:5], 6, v[4:5]
	s_addc_u32 s1, s9, 0
	v_lshl_add_u64 v[162:163], s[40:41], 0, v[4:5]
	s_add_u32 s54, s10, 0x100
	v_mov_b32_e32 v4, 0
	v_lshl_add_u64 v[160:161], s[40:41], 0, v[6:7]
	v_lshl_add_u64 v[164:165], s[0:1], 0, v[156:157]
	v_lshl_add_u64 v[166:167], s[0:1], 0, v[158:159]
	s_addc_u32 s55, s11, 0
	s_mov_b32 s58, -2
	s_mov_b64 s[10:11], 0
	s_branch .LpeelC

.LpeelC:
	s_add_u32 s0, s8, s10
	s_addc_u32 s1, s9, s11
	s_add_u32 s0, s0, 0x100
	s_addc_u32 s1, s1, 0
	s_add_u32 s59, s54, s10
	s_addc_u32 s60, s55, s11
	s_add_i32 s61, 0, 0x10000
	s_cmpk_eq_i32 s10, 0x700
	s_cselect_b32 s13, s3, s1
	s_cselect_b32 s12, s21, s0
	s_cselect_b32 s1, s47, s60
	s_cselect_b32 s0, s53, s59
	s_add_i32 s59, 0, 0x14000
	v_add_u32_e32 v168, s61, v188
	v_add_u32_e32 v176, s59, v188
	ds_read_b128 v[132:135], v168
	ds_read_b128 v[136:139], v168 offset:1024
	ds_read_b128 v[140:143], v168 offset:2048
	ds_read_b128 v[168:171], v168 offset:3072
	ds_read_b128 v[172:175], v176
	ds_read_b128 v[194:197], v176 offset:1024
	ds_read_b128 v[198:201], v176 offset:2048
	ds_read_b128 v[202:205], v176 offset:3072
	v_lshl_add_u64 v[176:177], v[164:165], 0, s[10:11]
	s_add_i32 m0, s18, 0xc000
	ds_read_b128 v[214:217], v190
	ds_read_b128 v[218:221], v190 offset:1024
	ds_read_b128 v[222:225], v190 offset:2048
	ds_read_b128 v[226:229], v190 offset:3072
	ds_read_b128 v[230:233], v190 offset:4096
	ds_read_b128 v[234:237], v190 offset:5120
	ds_read_b128 v[238:241], v190 offset:6144
	ds_read_b128 v[242:245], v190 offset:7168
	global_load_lds_dwordx4 v[176:177], off
	v_lshl_add_u64 v[176:177], v[166:167], 0, s[10:11]
	s_add_i32 m0, s18, 0xe000
	s_nop 0
	global_load_lds_dwordx4 v[176:177], off
	s_waitcnt vmcnt(8)
	s_waitcnt lgkmcnt(0)
	s_barrier
	s_setprio 1
	s_waitcnt lgkmcnt(0)
	v_mfma_f32_16x16x32_bf16 v[128:131], v[132:135], v[214:217], 0
	v_mfma_f32_16x16x32_bf16 v[124:127], v[140:143], v[214:217], 0
	v_mfma_f32_16x16x32_bf16 v[112:115], v[132:135], v[222:225], 0
	v_mfma_f32_16x16x32_bf16 v[108:111], v[140:143], v[222:225], 0
	v_mfma_f32_16x16x32_bf16 v[96:99], v[132:135], v[230:233], 0
	v_mfma_f32_16x16x32_bf16 v[92:95], v[140:143], v[230:233], 0
	v_mfma_f32_16x16x32_bf16 v[80:83], v[132:135], v[238:241], 0
	v_mfma_f32_16x16x32_bf16 v[76:79], v[140:143], v[238:241], 0
	v_mfma_f32_16x16x32_bf16 v[128:131], v[136:139], v[218:221], v[128:131]
	v_mfma_f32_16x16x32_bf16 v[124:127], v[168:171], v[218:221], v[124:127]
	v_mfma_f32_16x16x32_bf16 v[112:115], v[136:139], v[226:229], v[112:115]
	v_mfma_f32_16x16x32_bf16 v[108:111], v[168:171], v[226:229], v[108:111]
	v_mfma_f32_16x16x32_bf16 v[96:99], v[136:139], v[234:237], v[96:99]
	v_mfma_f32_16x16x32_bf16 v[92:95], v[168:171], v[234:237], v[92:95]
	v_mfma_f32_16x16x32_bf16 v[80:83], v[136:139], v[242:245], v[80:83]
	v_mfma_f32_16x16x32_bf16 v[76:79], v[168:171], v[242:245], v[76:79]
	s_setprio 0
	s_setprio 1
	v_mfma_f32_16x16x32_bf16 v[120:123], v[172:175], v[214:217], 0
	v_mfma_f32_16x16x32_bf16 v[116:119], v[198:201], v[214:217], 0
	v_mfma_f32_16x16x32_bf16 v[104:107], v[172:175], v[222:225], 0
	v_mfma_f32_16x16x32_bf16 v[100:103], v[198:201], v[222:225], 0
	v_mfma_f32_16x16x32_bf16 v[88:91], v[172:175], v[230:233], 0
	v_mfma_f32_16x16x32_bf16 v[84:87], v[198:201], v[230:233], 0
	v_mfma_f32_16x16x32_bf16 v[72:75], v[172:175], v[238:241], 0
	v_mfma_f32_16x16x32_bf16 v[68:71], v[198:201], v[238:241], 0
	v_mfma_f32_16x16x32_bf16 v[120:123], v[194:197], v[218:221], v[120:123]
	v_mfma_f32_16x16x32_bf16 v[116:119], v[202:205], v[218:221], v[116:119]
	v_mfma_f32_16x16x32_bf16 v[104:107], v[194:197], v[226:229], v[104:107]
	v_mfma_f32_16x16x32_bf16 v[100:103], v[202:205], v[226:229], v[100:103]
	v_mfma_f32_16x16x32_bf16 v[88:91], v[194:197], v[234:237], v[88:91]
	v_mfma_f32_16x16x32_bf16 v[84:87], v[202:205], v[234:237], v[84:87]
	v_mfma_f32_16x16x32_bf16 v[72:75], v[194:197], v[242:245], v[72:75]
	v_mfma_f32_16x16x32_bf16 v[68:71], v[202:205], v[242:245], v[68:71]
	s_setprio 0
	s_barrier
	s_add_i32 s60, s61, s15
	v_lshl_add_u64 v[176:177], s[0:1], 0, v[148:149]
	s_mov_b32 m0, s60
	ds_read_b128 v[214:217], v190 offset:16384
	ds_read_b128 v[218:221], v190 offset:17408
	ds_read_b128 v[222:225], v190 offset:18432
	ds_read_b128 v[226:229], v190 offset:19456
	ds_read_b128 v[230:233], v190 offset:20480
	ds_read_b128 v[234:237], v190 offset:21504
	ds_read_b128 v[238:241], v190 offset:22528
	ds_read_b128 v[242:245], v190 offset:23552
	global_load_lds_dwordx4 v[176:177], off
	s_add_i32 m0, s60, 0x2000
	s_add_u32 s60, s0, 0x40000
	v_lshl_add_u64 v[180:181], s[0:1], 0, v[144:145]
	s_addc_u32 s61, s1, 0
	s_add_i32 s59, s59, s15
	global_load_lds_dwordx4 v[180:181], off
	v_lshl_add_u64 v[182:183], s[60:61], 0, v[148:149]
	s_mov_b32 m0, s59
	v_lshl_add_u64 v[184:185], s[12:13], 0, v[146:147]
	global_load_lds_dwordx4 v[182:183], off
	v_lshl_add_u64 v[182:183], s[60:61], 0, v[144:145]
	s_add_i32 m0, s59, 0x2000
	s_nop 0
	global_load_lds_dwordx4 v[182:183], off
	v_lshl_add_u64 v[182:183], s[12:13], 0, v[150:151]
	s_mov_b32 m0, s18
	s_nop 0
	global_load_lds_dwordx4 v[182:183], off
	s_mov_b32 m0, s19
	s_nop 0
	global_load_lds_dwordx4 v[184:185], off
	s_waitcnt vmcnt(8)
	s_waitcnt lgkmcnt(0)
	s_barrier
	s_setprio 1
	s_waitcnt lgkmcnt(0)
	v_mfma_f32_16x16x32_bf16 v[64:67], v[132:135], v[214:217], 0
	v_mfma_f32_16x16x32_bf16 v[60:63], v[140:143], v[214:217], 0
	v_mfma_f32_16x16x32_bf16 v[48:51], v[132:135], v[222:225], 0
	v_mfma_f32_16x16x32_bf16 v[44:47], v[140:143], v[222:225], 0
	v_mfma_f32_16x16x32_bf16 v[32:35], v[132:135], v[230:233], 0
	v_mfma_f32_16x16x32_bf16 v[28:31], v[140:143], v[230:233], 0
	v_mfma_f32_16x16x32_bf16 v[16:19], v[132:135], v[238:241], 0
	v_mfma_f32_16x16x32_bf16 v[12:15], v[140:143], v[238:241], 0
	v_mfma_f32_16x16x32_bf16 v[64:67], v[136:139], v[218:221], v[64:67]
	v_mfma_f32_16x16x32_bf16 v[60:63], v[168:171], v[218:221], v[60:63]
	v_mfma_f32_16x16x32_bf16 v[48:51], v[136:139], v[226:229], v[48:51]
	v_mfma_f32_16x16x32_bf16 v[44:47], v[168:171], v[226:229], v[44:47]
	v_mfma_f32_16x16x32_bf16 v[32:35], v[136:139], v[234:237], v[32:35]
	v_mfma_f32_16x16x32_bf16 v[28:31], v[168:171], v[234:237], v[28:31]
	v_mfma_f32_16x16x32_bf16 v[16:19], v[136:139], v[242:245], v[16:19]
	v_mfma_f32_16x16x32_bf16 v[12:15], v[168:171], v[242:245], v[12:15]
	s_setprio 0
	s_setprio 1
	v_mfma_f32_16x16x32_bf16 v[56:59], v[172:175], v[214:217], 0
	v_mfma_f32_16x16x32_bf16 v[52:55], v[198:201], v[214:217], 0
	v_mfma_f32_16x16x32_bf16 v[40:43], v[172:175], v[222:225], 0
	v_mfma_f32_16x16x32_bf16 v[36:39], v[198:201], v[222:225], 0
	v_mfma_f32_16x16x32_bf16 v[24:27], v[172:175], v[230:233], 0
	v_mfma_f32_16x16x32_bf16 v[20:23], v[198:201], v[230:233], 0
	v_mfma_f32_16x16x32_bf16 v[8:11], v[172:175], v[238:241], 0
	v_mfma_f32_16x16x32_bf16 v[4:7], v[198:201], v[238:241], 0
	v_mfma_f32_16x16x32_bf16 v[56:59], v[194:197], v[218:221], v[56:59]
	v_mfma_f32_16x16x32_bf16 v[52:55], v[202:205], v[218:221], v[52:55]
	v_mfma_f32_16x16x32_bf16 v[40:43], v[194:197], v[226:229], v[40:43]
	v_mfma_f32_16x16x32_bf16 v[36:39], v[202:205], v[226:229], v[36:39]
	v_mfma_f32_16x16x32_bf16 v[24:27], v[194:197], v[234:237], v[24:27]
	v_mfma_f32_16x16x32_bf16 v[20:23], v[202:205], v[234:237], v[20:23]
	v_mfma_f32_16x16x32_bf16 v[8:11], v[194:197], v[242:245], v[8:11]
	v_mfma_f32_16x16x32_bf16 v[4:7], v[202:205], v[242:245], v[4:7]
	s_setprio 0
	s_barrier
	s_add_i32 s59, 0, 0x18000
	s_add_i32 s60, 0, 0x1c000
	v_add_u32_e32 v168, s59, v188
	v_add_u32_e32 v193, s60, v188
	ds_read_b128 v[132:135], v168
	ds_read_b128 v[136:139], v168 offset:1024
	ds_read_b128 v[140:143], v168 offset:2048
	ds_read_b128 v[168:171], v168 offset:3072
	ds_read_b128 v[172:175], v193
	ds_read_b128 v[194:197], v193 offset:1024
	ds_read_b128 v[198:201], v193 offset:2048
	ds_read_b128 v[202:205], v193 offset:3072
	s_add_u32 s12, s12, 0x40000
	s_addc_u32 s13, s13, 0
	s_mov_b32 m0, s23
	v_lshl_add_u64 v[206:207], s[12:13], 0, v[150:151]
	ds_read_b128 v[214:217], v190 offset:32768
	ds_read_b128 v[218:221], v190 offset:33792
	ds_read_b128 v[222:225], v190 offset:34816
	ds_read_b128 v[226:229], v190 offset:35840
	ds_read_b128 v[230:233], v190 offset:36864
	ds_read_b128 v[234:237], v190 offset:37888
	ds_read_b128 v[238:241], v190 offset:38912
	ds_read_b128 v[242:245], v190 offset:39936
	global_load_lds_dwordx4 v[206:207], off
	v_lshl_add_u64 v[206:207], s[12:13], 0, v[146:147]
	s_mov_b32 m0, s24
	s_nop 0
	global_load_lds_dwordx4 v[206:207], off
	s_waitcnt vmcnt(8)
	s_waitcnt lgkmcnt(0)
	s_barrier
	s_setprio 1
	s_waitcnt lgkmcnt(0)
	v_mfma_f32_16x16x32_bf16 v[128:131], v[132:135], v[214:217], v[128:131]
	v_mfma_f32_16x16x32_bf16 v[124:127], v[140:143], v[214:217], v[124:127]
	v_mfma_f32_16x16x32_bf16 v[112:115], v[132:135], v[222:225], v[112:115]
	v_mfma_f32_16x16x32_bf16 v[108:111], v[140:143], v[222:225], v[108:111]
	v_mfma_f32_16x16x32_bf16 v[96:99], v[132:135], v[230:233], v[96:99]
	v_mfma_f32_16x16x32_bf16 v[92:95], v[140:143], v[230:233], v[92:95]
	v_mfma_f32_16x16x32_bf16 v[80:83], v[132:135], v[238:241], v[80:83]
	v_mfma_f32_16x16x32_bf16 v[76:79], v[140:143], v[238:241], v[76:79]
	v_mfma_f32_16x16x32_bf16 v[128:131], v[136:139], v[218:221], v[128:131]
	v_mfma_f32_16x16x32_bf16 v[124:127], v[168:171], v[218:221], v[124:127]
	v_mfma_f32_16x16x32_bf16 v[112:115], v[136:139], v[226:229], v[112:115]
	v_mfma_f32_16x16x32_bf16 v[108:111], v[168:171], v[226:229], v[108:111]
	v_mfma_f32_16x16x32_bf16 v[96:99], v[136:139], v[234:237], v[96:99]
	v_mfma_f32_16x16x32_bf16 v[92:95], v[168:171], v[234:237], v[92:95]
	v_mfma_f32_16x16x32_bf16 v[80:83], v[136:139], v[242:245], v[80:83]
	v_mfma_f32_16x16x32_bf16 v[76:79], v[168:171], v[242:245], v[76:79]
	s_setprio 0
	s_setprio 1
	v_mfma_f32_16x16x32_bf16 v[120:123], v[172:175], v[214:217], v[120:123]
	v_mfma_f32_16x16x32_bf16 v[116:119], v[198:201], v[214:217], v[116:119]
	v_mfma_f32_16x16x32_bf16 v[104:107], v[172:175], v[222:225], v[104:107]
	v_mfma_f32_16x16x32_bf16 v[100:103], v[198:201], v[222:225], v[100:103]
	v_mfma_f32_16x16x32_bf16 v[88:91], v[172:175], v[230:233], v[88:91]
	v_mfma_f32_16x16x32_bf16 v[84:87], v[198:201], v[230:233], v[84:87]
	v_mfma_f32_16x16x32_bf16 v[72:75], v[172:175], v[238:241], v[72:75]
	v_mfma_f32_16x16x32_bf16 v[68:71], v[198:201], v[238:241], v[68:71]
	v_mfma_f32_16x16x32_bf16 v[120:123], v[194:197], v[218:221], v[120:123]
	v_mfma_f32_16x16x32_bf16 v[116:119], v[202:205], v[218:221], v[116:119]
	v_mfma_f32_16x16x32_bf16 v[104:107], v[194:197], v[226:229], v[104:107]
	v_mfma_f32_16x16x32_bf16 v[100:103], v[202:205], v[226:229], v[100:103]
	v_mfma_f32_16x16x32_bf16 v[88:91], v[194:197], v[234:237], v[88:91]
	v_mfma_f32_16x16x32_bf16 v[84:87], v[202:205], v[234:237], v[84:87]
	v_mfma_f32_16x16x32_bf16 v[72:75], v[194:197], v[242:245], v[72:75]
	v_mfma_f32_16x16x32_bf16 v[68:71], v[202:205], v[242:245], v[68:71]
	s_setprio 0
	s_barrier
	s_add_i32 s12, s59, s15
	v_lshl_add_u64 v[176:177], v[176:177], 0, s[34:35]
	s_mov_b32 m0, s12
	ds_read_b128 v[214:217], v190 offset:49152
	ds_read_b128 v[218:221], v190 offset:50176
	ds_read_b128 v[222:225], v190 offset:51200
	ds_read_b128 v[226:229], v190 offset:52224
	ds_read_b128 v[230:233], v190 offset:53248
	ds_read_b128 v[234:237], v190 offset:54272
	ds_read_b128 v[238:241], v190 offset:55296
	ds_read_b128 v[242:245], v190 offset:56320
	global_load_lds_dwordx4 v[176:177], off
	s_add_i32 m0, s12, 0x2000
	s_add_u32 s0, s0, 0x40080
	v_lshl_add_u64 v[176:177], v[180:181], 0, s[34:35]
	s_addc_u32 s1, s1, 0
	s_add_i32 s12, s60, s15
	global_load_lds_dwordx4 v[176:177], off
	v_lshl_add_u64 v[176:177], s[0:1], 0, v[148:149]
	s_mov_b32 m0, s12
	s_nop 0
	global_load_lds_dwordx4 v[176:177], off
	v_lshl_add_u64 v[176:177], s[0:1], 0, v[144:145]
	s_add_i32 m0, s12, 0x2000
	s_nop 0
	global_load_lds_dwordx4 v[176:177], off
	v_lshl_add_u64 v[176:177], v[182:183], 0, s[34:35]
	s_mov_b32 m0, s25
	s_nop 0
	global_load_lds_dwordx4 v[176:177], off
	v_lshl_add_u64 v[176:177], v[184:185], 0, s[34:35]
	s_mov_b32 m0, s30
	s_nop 0
	global_load_lds_dwordx4 v[176:177], off
	s_waitcnt vmcnt(8)
	s_waitcnt lgkmcnt(0)
	s_barrier
	s_setprio 1
	s_waitcnt lgkmcnt(0)
	v_mfma_f32_16x16x32_bf16 v[64:67], v[132:135], v[214:217], v[64:67]
	v_mfma_f32_16x16x32_bf16 v[60:63], v[140:143], v[214:217], v[60:63]
	v_mfma_f32_16x16x32_bf16 v[48:51], v[132:135], v[222:225], v[48:51]
	v_mfma_f32_16x16x32_bf16 v[44:47], v[140:143], v[222:225], v[44:47]
	v_mfma_f32_16x16x32_bf16 v[32:35], v[132:135], v[230:233], v[32:35]
	v_mfma_f32_16x16x32_bf16 v[28:31], v[140:143], v[230:233], v[28:31]
	v_mfma_f32_16x16x32_bf16 v[16:19], v[132:135], v[238:241], v[16:19]
	v_mfma_f32_16x16x32_bf16 v[12:15], v[140:143], v[238:241], v[12:15]
	v_mfma_f32_16x16x32_bf16 v[64:67], v[136:139], v[218:221], v[64:67]
	v_mfma_f32_16x16x32_bf16 v[60:63], v[168:171], v[218:221], v[60:63]
	v_mfma_f32_16x16x32_bf16 v[48:51], v[136:139], v[226:229], v[48:51]
	v_mfma_f32_16x16x32_bf16 v[44:47], v[168:171], v[226:229], v[44:47]
	v_mfma_f32_16x16x32_bf16 v[32:35], v[136:139], v[234:237], v[32:35]
	v_mfma_f32_16x16x32_bf16 v[28:31], v[168:171], v[234:237], v[28:31]
	v_mfma_f32_16x16x32_bf16 v[16:19], v[136:139], v[242:245], v[16:19]
	v_mfma_f32_16x16x32_bf16 v[12:15], v[168:171], v[242:245], v[12:15]
	s_setprio 0
	s_setprio 1
	v_mfma_f32_16x16x32_bf16 v[56:59], v[172:175], v[214:217], v[56:59]
	v_mfma_f32_16x16x32_bf16 v[52:55], v[198:201], v[214:217], v[52:55]
	v_mfma_f32_16x16x32_bf16 v[40:43], v[172:175], v[222:225], v[40:43]
	v_mfma_f32_16x16x32_bf16 v[36:39], v[198:201], v[222:225], v[36:39]
	v_mfma_f32_16x16x32_bf16 v[24:27], v[172:175], v[230:233], v[24:27]
	v_mfma_f32_16x16x32_bf16 v[20:23], v[198:201], v[230:233], v[20:23]
	v_mfma_f32_16x16x32_bf16 v[8:11], v[172:175], v[238:241], v[8:11]
	v_mfma_f32_16x16x32_bf16 v[4:7], v[198:201], v[238:241], v[4:7]
	v_mfma_f32_16x16x32_bf16 v[56:59], v[194:197], v[218:221], v[56:59]
	v_mfma_f32_16x16x32_bf16 v[52:55], v[202:205], v[218:221], v[52:55]
	v_mfma_f32_16x16x32_bf16 v[40:43], v[194:197], v[226:229], v[40:43]
	v_mfma_f32_16x16x32_bf16 v[36:39], v[202:205], v[226:229], v[36:39]
	v_mfma_f32_16x16x32_bf16 v[24:27], v[194:197], v[234:237], v[24:27]
	v_mfma_f32_16x16x32_bf16 v[20:23], v[202:205], v[234:237], v[20:23]
	v_mfma_f32_16x16x32_bf16 v[8:11], v[194:197], v[242:245], v[8:11]
	v_mfma_f32_16x16x32_bf16 v[4:7], v[202:205], v[242:245], v[4:7]
	s_setprio 0
	s_barrier
	s_add_i32 s58, s58, 2
	s_add_u32 s10, s10, 0x100
	s_addc_u32 s11, s11, 0
	s_cmp_gt_u32 s58, 13
	s_cbranch_scc1 .LBB0_441
	s_branch .LBB0_439

.LBB0_465:
	s_ashr_i32 s15, s14, 31
	s_lshl_b64 s[18:19], s[14:15], 18
	s_add_u32 s36, s23, s18
	s_addc_u32 s37, s24, s19
	s_and_b64 s[18:19], s[16:17], exec
	s_cselect_b32 s15, s37, s43
	s_cselect_b32 s18, s36, s42
	s_ashr_i32 s13, s12, 31
	s_lshl_b64 s[40:41], s[12:13], 18
	s_add_u32 s40, s2, s40
	s_addc_u32 s41, s3, s41
	s_and_b64 s[46:47], s[16:17], exec
	s_cselect_b32 s19, s41, s1
	s_cselect_b32 s52, s40, s0
	s_lshl_b32 s13, s44, 8
	v_add_u32_e32 v4, s13, v154
	v_ashrrev_i32_e32 v5, 31, v4
	v_lshlrev_b64 v[6:7], 5, v[4:5]
	v_or_b32_e32 v4, 16, v4
	v_ashrrev_i32_e32 v5, 31, v4
	s_add_u32 s44, s42, 0x20080
	v_lshlrev_b64 v[4:5], 5, v[4:5]
	s_addc_u32 s45, s43, 0
	v_lshl_add_u64 v[146:147], s[8:9], 0, v[4:5]
	s_add_u32 s53, s0, 0x100
	v_mov_b32_e32 v4, 0
	v_lshl_add_u64 v[144:145], s[8:9], 0, v[6:7]
	v_lshl_add_u64 v[148:149], s[44:45], 0, v[140:141]
	v_lshl_add_u64 v[150:151], s[44:45], 0, v[142:143]
	s_addc_u32 s54, s1, 0
	s_mov_b32 s55, -2
	s_mov_b64 s[44:45], 0
	s_branch .LpeelD

.LpeelD:
	s_add_u32 s0, s42, s44
	s_addc_u32 s1, s43, s45
	s_add_u32 s0, s0, 0x100
	s_addc_u32 s1, s1, 0
	s_add_u32 s58, s53, s44
	s_addc_u32 s59, s54, s45
	s_add_i32 s60, 0, 0x10000
	s_cmpk_eq_i32 s44, 0x300
	s_cselect_b32 s47, s15, s1
	s_cselect_b32 s46, s18, s0
	v_add_u32_e32 v159, s60, v153
	s_cselect_b32 s1, s19, s59
	s_cselect_b32 s0, s52, s58
	s_add_i32 s61, 0, 0x14000
	ds_read_b128 v[160:163], v159
	ds_read_b128 v[164:167], v159 offset:1024
	ds_read_b128 v[168:171], v159 offset:2048
	ds_read_b128 v[172:175], v159 offset:3072
	v_add_u32_e32 v159, s61, v153
	ds_read_b128 v[176:179], v159
	ds_read_b128 v[188:191], v159 offset:1024
	ds_read_b128 v[192:195], v159 offset:2048
	ds_read_b128 v[196:199], v159 offset:3072
	v_lshl_add_u64 v[180:181], v[148:149], 0, s[44:45]
	s_add_i32 m0, s25, 0xc000
	ds_read_b128 v[200:203], v155
	ds_read_b128 v[204:207], v155 offset:1024
	ds_read_b128 v[214:217], v155 offset:2048
	ds_read_b128 v[218:221], v155 offset:3072
	ds_read_b128 v[222:225], v155 offset:4096
	ds_read_b128 v[226:229], v155 offset:5120
	ds_read_b128 v[230:233], v155 offset:6144
	ds_read_b128 v[234:237], v155 offset:7168
	global_load_lds_dwordx4 v[180:181], off
	v_lshl_add_u64 v[180:181], v[150:151], 0, s[44:45]
	s_add_i32 m0, s25, 0xe000
	s_nop 0
	global_load_lds_dwordx4 v[180:181], off
	s_waitcnt vmcnt(8)
	s_waitcnt lgkmcnt(0)
	s_barrier
	s_setprio 1
	s_waitcnt lgkmcnt(0)
	v_mfma_f32_16x16x32_bf16 v[128:131], v[160:163], v[200:203], 0
	v_mfma_f32_16x16x32_bf16 v[124:127], v[168:171], v[200:203], 0
	v_mfma_f32_16x16x32_bf16 v[112:115], v[160:163], v[214:217], 0
	v_mfma_f32_16x16x32_bf16 v[108:111], v[168:171], v[214:217], 0
	v_mfma_f32_16x16x32_bf16 v[96:99], v[160:163], v[222:225], 0
	v_mfma_f32_16x16x32_bf16 v[92:95], v[168:171], v[222:225], 0
	v_mfma_f32_16x16x32_bf16 v[80:83], v[160:163], v[230:233], 0
	v_mfma_f32_16x16x32_bf16 v[76:79], v[168:171], v[230:233], 0
	v_mfma_f32_16x16x32_bf16 v[128:131], v[164:167], v[204:207], v[128:131]
	v_mfma_f32_16x16x32_bf16 v[124:127], v[172:175], v[204:207], v[124:127]
	v_mfma_f32_16x16x32_bf16 v[112:115], v[164:167], v[218:221], v[112:115]
	v_mfma_f32_16x16x32_bf16 v[108:111], v[172:175], v[218:221], v[108:111]
	v_mfma_f32_16x16x32_bf16 v[96:99], v[164:167], v[226:229], v[96:99]
	v_mfma_f32_16x16x32_bf16 v[92:95], v[172:175], v[226:229], v[92:95]
	v_mfma_f32_16x16x32_bf16 v[80:83], v[164:167], v[234:237], v[80:83]
	v_mfma_f32_16x16x32_bf16 v[76:79], v[172:175], v[234:237], v[76:79]
	s_setprio 0
	s_setprio 1
	v_mfma_f32_16x16x32_bf16 v[120:123], v[176:179], v[200:203], 0
	v_mfma_f32_16x16x32_bf16 v[116:119], v[192:195], v[200:203], 0
	v_mfma_f32_16x16x32_bf16 v[104:107], v[176:179], v[214:217], 0
	v_mfma_f32_16x16x32_bf16 v[100:103], v[192:195], v[214:217], 0
	v_mfma_f32_16x16x32_bf16 v[88:91], v[176:179], v[222:225], 0
	v_mfma_f32_16x16x32_bf16 v[84:87], v[192:195], v[222:225], 0
	v_mfma_f32_16x16x32_bf16 v[72:75], v[176:179], v[230:233], 0
	v_mfma_f32_16x16x32_bf16 v[68:71], v[192:195], v[230:233], 0
	v_mfma_f32_16x16x32_bf16 v[120:123], v[188:191], v[204:207], v[120:123]
	v_mfma_f32_16x16x32_bf16 v[116:119], v[196:199], v[204:207], v[116:119]
	v_mfma_f32_16x16x32_bf16 v[104:107], v[188:191], v[218:221], v[104:107]
	v_mfma_f32_16x16x32_bf16 v[100:103], v[196:199], v[218:221], v[100:103]
	v_mfma_f32_16x16x32_bf16 v[88:91], v[188:191], v[226:229], v[88:91]
	v_mfma_f32_16x16x32_bf16 v[84:87], v[196:199], v[226:229], v[84:87]
	v_mfma_f32_16x16x32_bf16 v[72:75], v[188:191], v[234:237], v[72:75]
	v_mfma_f32_16x16x32_bf16 v[68:71], v[196:199], v[234:237], v[68:71]
	s_setprio 0
	s_barrier
	s_add_i32 s58, s60, s21
	v_lshl_add_u64 v[180:181], s[0:1], 0, v[136:137]
	s_mov_b32 m0, s58
	ds_read_b128 v[200:203], v155 offset:16384
	ds_read_b128 v[204:207], v155 offset:17408
	ds_read_b128 v[214:217], v155 offset:18432
	ds_read_b128 v[218:221], v155 offset:19456
	ds_read_b128 v[222:225], v155 offset:20480
	ds_read_b128 v[226:229], v155 offset:21504
	ds_read_b128 v[230:233], v155 offset:22528
	ds_read_b128 v[234:237], v155 offset:23552
	global_load_lds_dwordx4 v[180:181], off
	s_add_i32 m0, s58, 0x2000
	s_add_u32 s58, s0, 0x20000
	v_lshl_add_u64 v[182:183], s[0:1], 0, v[132:133]
	s_addc_u32 s59, s1, 0
	s_add_i32 s60, s61, s21
	global_load_lds_dwordx4 v[182:183], off
	v_lshl_add_u64 v[184:185], s[58:59], 0, v[136:137]
	s_mov_b32 m0, s60
	v_lshl_add_u64 v[238:239], s[46:47], 0, v[134:135]
	global_load_lds_dwordx4 v[184:185], off
	v_lshl_add_u64 v[184:185], s[58:59], 0, v[132:133]
	s_add_i32 m0, s60, 0x2000
	s_nop 0
	global_load_lds_dwordx4 v[184:185], off
	v_lshl_add_u64 v[184:185], s[46:47], 0, v[138:139]
	s_mov_b32 m0, s25
	s_nop 0
	global_load_lds_dwordx4 v[184:185], off
	s_mov_b32 m0, s30
	s_nop 0
	global_load_lds_dwordx4 v[238:239], off
	s_waitcnt vmcnt(8)
	s_waitcnt lgkmcnt(0)
	s_barrier
	s_setprio 1
	s_waitcnt lgkmcnt(0)
	v_mfma_f32_16x16x32_bf16 v[64:67], v[160:163], v[200:203], 0
	v_mfma_f32_16x16x32_bf16 v[60:63], v[168:171], v[200:203], 0
	v_mfma_f32_16x16x32_bf16 v[48:51], v[160:163], v[214:217], 0
	v_mfma_f32_16x16x32_bf16 v[44:47], v[168:171], v[214:217], 0
	v_mfma_f32_16x16x32_bf16 v[32:35], v[160:163], v[222:225], 0
	v_mfma_f32_16x16x32_bf16 v[28:31], v[168:171], v[222:225], 0
	v_mfma_f32_16x16x32_bf16 v[16:19], v[160:163], v[230:233], 0
	v_mfma_f32_16x16x32_bf16 v[12:15], v[168:171], v[230:233], 0
	v_mfma_f32_16x16x32_bf16 v[64:67], v[164:167], v[204:207], v[64:67]
	v_mfma_f32_16x16x32_bf16 v[60:63], v[172:175], v[204:207], v[60:63]
	v_mfma_f32_16x16x32_bf16 v[48:51], v[164:167], v[218:221], v[48:51]
	v_mfma_f32_16x16x32_bf16 v[44:47], v[172:175], v[218:221], v[44:47]
	v_mfma_f32_16x16x32_bf16 v[32:35], v[164:167], v[226:229], v[32:35]
	v_mfma_f32_16x16x32_bf16 v[28:31], v[172:175], v[226:229], v[28:31]
	v_mfma_f32_16x16x32_bf16 v[16:19], v[164:167], v[234:237], v[16:19]
	v_mfma_f32_16x16x32_bf16 v[12:15], v[172:175], v[234:237], v[12:15]
	s_setprio 0
	s_setprio 1
	v_mfma_f32_16x16x32_bf16 v[56:59], v[176:179], v[200:203], 0
	v_mfma_f32_16x16x32_bf16 v[52:55], v[192:195], v[200:203], 0
	v_mfma_f32_16x16x32_bf16 v[40:43], v[176:179], v[214:217], 0
	v_mfma_f32_16x16x32_bf16 v[36:39], v[192:195], v[214:217], 0
	v_mfma_f32_16x16x32_bf16 v[24:27], v[176:179], v[222:225], 0
	v_mfma_f32_16x16x32_bf16 v[20:23], v[192:195], v[222:225], 0
	v_mfma_f32_16x16x32_bf16 v[8:11], v[176:179], v[230:233], 0
	v_mfma_f32_16x16x32_bf16 v[4:7], v[192:195], v[230:233], 0
	v_mfma_f32_16x16x32_bf16 v[56:59], v[188:191], v[204:207], v[56:59]
	v_mfma_f32_16x16x32_bf16 v[52:55], v[196:199], v[204:207], v[52:55]
	v_mfma_f32_16x16x32_bf16 v[40:43], v[188:191], v[218:221], v[40:43]
	v_mfma_f32_16x16x32_bf16 v[36:39], v[196:199], v[218:221], v[36:39]
	v_mfma_f32_16x16x32_bf16 v[24:27], v[188:191], v[226:229], v[24:27]
	v_mfma_f32_16x16x32_bf16 v[20:23], v[196:199], v[226:229], v[20:23]
	v_mfma_f32_16x16x32_bf16 v[8:11], v[188:191], v[234:237], v[8:11]
	v_mfma_f32_16x16x32_bf16 v[4:7], v[196:199], v[234:237], v[4:7]
	s_setprio 0
	s_barrier
	s_add_i32 s58, 0, 0x18000
	v_add_u32_e32 v159, s58, v153
	s_add_i32 s59, 0, 0x1c000
	ds_read_b128 v[160:163], v159
	ds_read_b128 v[164:167], v159 offset:1024
	ds_read_b128 v[168:171], v159 offset:2048
	ds_read_b128 v[172:175], v159 offset:3072
	v_add_u32_e32 v159, s59, v153
	ds_read_b128 v[176:179], v159
	ds_read_b128 v[188:191], v159 offset:1024
	ds_read_b128 v[192:195], v159 offset:2048
	ds_read_b128 v[196:199], v159 offset:3072
	s_add_u32 s46, s46, 0x20000
	s_addc_u32 s47, s47, 0
	s_mov_b32 m0, s31
	v_lshl_add_u64 v[240:241], s[46:47], 0, v[138:139]
	ds_read_b128 v[200:203], v155 offset:32768
	ds_read_b128 v[204:207], v155 offset:33792
	ds_read_b128 v[214:217], v155 offset:34816
	ds_read_b128 v[218:221], v155 offset:35840
	ds_read_b128 v[222:225], v155 offset:36864
	ds_read_b128 v[226:229], v155 offset:37888
	ds_read_b128 v[230:233], v155 offset:38912
	ds_read_b128 v[234:237], v155 offset:39936
	global_load_lds_dwordx4 v[240:241], off
	v_lshl_add_u64 v[240:241], s[46:47], 0, v[134:135]
	s_mov_b32 m0, s33
	s_nop 0
	global_load_lds_dwordx4 v[240:241], off
	s_waitcnt vmcnt(8)
	s_waitcnt lgkmcnt(0)
	s_barrier
	s_setprio 1
	s_waitcnt lgkmcnt(0)
	v_mfma_f32_16x16x32_bf16 v[128:131], v[160:163], v[200:203], v[128:131]
	v_mfma_f32_16x16x32_bf16 v[124:127], v[168:171], v[200:203], v[124:127]
	v_mfma_f32_16x16x32_bf16 v[112:115], v[160:163], v[214:217], v[112:115]
	v_mfma_f32_16x16x32_bf16 v[108:111], v[168:171], v[214:217], v[108:111]
	v_mfma_f32_16x16x32_bf16 v[96:99], v[160:163], v[222:225], v[96:99]
	v_mfma_f32_16x16x32_bf16 v[92:95], v[168:171], v[222:225], v[92:95]
	v_mfma_f32_16x16x32_bf16 v[80:83], v[160:163], v[230:233], v[80:83]
	v_mfma_f32_16x16x32_bf16 v[76:79], v[168:171], v[230:233], v[76:79]
	v_mfma_f32_16x16x32_bf16 v[128:131], v[164:167], v[204:207], v[128:131]
	v_mfma_f32_16x16x32_bf16 v[124:127], v[172:175], v[204:207], v[124:127]
	v_mfma_f32_16x16x32_bf16 v[112:115], v[164:167], v[218:221], v[112:115]
	v_mfma_f32_16x16x32_bf16 v[108:111], v[172:175], v[218:221], v[108:111]
	v_mfma_f32_16x16x32_bf16 v[96:99], v[164:167], v[226:229], v[96:99]
	v_mfma_f32_16x16x32_bf16 v[92:95], v[172:175], v[226:229], v[92:95]
	v_mfma_f32_16x16x32_bf16 v[80:83], v[164:167], v[234:237], v[80:83]
	v_mfma_f32_16x16x32_bf16 v[76:79], v[172:175], v[234:237], v[76:79]
	s_setprio 0
	s_setprio 1
	v_mfma_f32_16x16x32_bf16 v[120:123], v[176:179], v[200:203], v[120:123]
	v_mfma_f32_16x16x32_bf16 v[116:119], v[192:195], v[200:203], v[116:119]
	v_mfma_f32_16x16x32_bf16 v[104:107], v[176:179], v[214:217], v[104:107]
	v_mfma_f32_16x16x32_bf16 v[100:103], v[192:195], v[214:217], v[100:103]
	v_mfma_f32_16x16x32_bf16 v[88:91], v[176:179], v[222:225], v[88:91]
	v_mfma_f32_16x16x32_bf16 v[84:87], v[192:195], v[222:225], v[84:87]
	v_mfma_f32_16x16x32_bf16 v[72:75], v[176:179], v[230:233], v[72:75]
	v_mfma_f32_16x16x32_bf16 v[68:71], v[192:195], v[230:233], v[68:71]
	v_mfma_f32_16x16x32_bf16 v[120:123], v[188:191], v[204:207], v[120:123]
	v_mfma_f32_16x16x32_bf16 v[116:119], v[196:199], v[204:207], v[116:119]
	v_mfma_f32_16x16x32_bf16 v[104:107], v[188:191], v[218:221], v[104:107]
	v_mfma_f32_16x16x32_bf16 v[100:103], v[196:199], v[218:221], v[100:103]
	v_mfma_f32_16x16x32_bf16 v[88:91], v[188:191], v[226:229], v[88:91]
	v_mfma_f32_16x16x32_bf16 v[84:87], v[196:199], v[226:229], v[84:87]
	v_mfma_f32_16x16x32_bf16 v[72:75], v[188:191], v[234:237], v[72:75]
	v_mfma_f32_16x16x32_bf16 v[68:71], v[196:199], v[234:237], v[68:71]
	s_setprio 0
	s_barrier
	s_add_i32 s46, s58, s21
	v_lshl_add_u64 v[180:181], v[180:181], 0, s[34:35]
	s_mov_b32 m0, s46
	ds_read_b128 v[200:203], v155 offset:49152
	ds_read_b128 v[204:207], v155 offset:50176
	ds_read_b128 v[214:217], v155 offset:51200
	ds_read_b128 v[218:221], v155 offset:52224
	ds_read_b128 v[222:225], v155 offset:53248
	ds_read_b128 v[226:229], v155 offset:54272
	ds_read_b128 v[230:233], v155 offset:55296
	ds_read_b128 v[234:237], v155 offset:56320
	global_load_lds_dwordx4 v[180:181], off
	s_add_i32 m0, s46, 0x2000
	s_add_u32 s0, s0, 0x20080
	v_lshl_add_u64 v[180:181], v[182:183], 0, s[34:35]
	s_addc_u32 s1, s1, 0
	s_add_i32 s46, s59, s21
	global_load_lds_dwordx4 v[180:181], off
	v_lshl_add_u64 v[180:181], s[0:1], 0, v[136:137]
	s_mov_b32 m0, s46
	s_nop 0
	global_load_lds_dwordx4 v[180:181], off
	v_lshl_add_u64 v[180:181], s[0:1], 0, v[132:133]
	s_add_i32 m0, s46, 0x2000
	s_nop 0
	global_load_lds_dwordx4 v[180:181], off
	v_lshl_add_u64 v[180:181], v[184:185], 0, s[34:35]
	s_mov_b32 m0, s48
	s_nop 0
	global_load_lds_dwordx4 v[180:181], off
	v_lshl_add_u64 v[180:181], v[238:239], 0, s[34:35]
	s_mov_b32 m0, s49
	s_nop 0
	global_load_lds_dwordx4 v[180:181], off
	s_waitcnt vmcnt(8)
	s_waitcnt lgkmcnt(0)
	s_barrier
	s_setprio 1
	s_waitcnt lgkmcnt(0)
	v_mfma_f32_16x16x32_bf16 v[64:67], v[160:163], v[200:203], v[64:67]
	v_mfma_f32_16x16x32_bf16 v[60:63], v[168:171], v[200:203], v[60:63]
	v_mfma_f32_16x16x32_bf16 v[48:51], v[160:163], v[214:217], v[48:51]
	v_mfma_f32_16x16x32_bf16 v[44:47], v[168:171], v[214:217], v[44:47]
	v_mfma_f32_16x16x32_bf16 v[32:35], v[160:163], v[222:225], v[32:35]
	v_mfma_f32_16x16x32_bf16 v[28:31], v[168:171], v[222:225], v[28:31]
	v_mfma_f32_16x16x32_bf16 v[16:19], v[160:163], v[230:233], v[16:19]
	v_mfma_f32_16x16x32_bf16 v[12:15], v[168:171], v[230:233], v[12:15]
	v_mfma_f32_16x16x32_bf16 v[64:67], v[164:167], v[204:207], v[64:67]
	v_mfma_f32_16x16x32_bf16 v[60:63], v[172:175], v[204:207], v[60:63]
	v_mfma_f32_16x16x32_bf16 v[48:51], v[164:167], v[218:221], v[48:51]
	v_mfma_f32_16x16x32_bf16 v[44:47], v[172:175], v[218:221], v[44:47]
	v_mfma_f32_16x16x32_bf16 v[32:35], v[164:167], v[226:229], v[32:35]
	v_mfma_f32_16x16x32_bf16 v[28:31], v[172:175], v[226:229], v[28:31]
	v_mfma_f32_16x16x32_bf16 v[16:19], v[164:167], v[234:237], v[16:19]
	v_mfma_f32_16x16x32_bf16 v[12:15], v[172:175], v[234:237], v[12:15]
	s_setprio 0
	s_setprio 1
	v_mfma_f32_16x16x32_bf16 v[56:59], v[176:179], v[200:203], v[56:59]
	v_mfma_f32_16x16x32_bf16 v[52:55], v[192:195], v[200:203], v[52:55]
	v_mfma_f32_16x16x32_bf16 v[40:43], v[176:179], v[214:217], v[40:43]
	v_mfma_f32_16x16x32_bf16 v[36:39], v[192:195], v[214:217], v[36:39]
	v_mfma_f32_16x16x32_bf16 v[24:27], v[176:179], v[222:225], v[24:27]
	v_mfma_f32_16x16x32_bf16 v[20:23], v[192:195], v[222:225], v[20:23]
	v_mfma_f32_16x16x32_bf16 v[8:11], v[176:179], v[230:233], v[8:11]
	v_mfma_f32_16x16x32_bf16 v[4:7], v[192:195], v[230:233], v[4:7]
	v_mfma_f32_16x16x32_bf16 v[56:59], v[188:191], v[204:207], v[56:59]
	v_mfma_f32_16x16x32_bf16 v[52:55], v[196:199], v[204:207], v[52:55]
	v_mfma_f32_16x16x32_bf16 v[40:43], v[188:191], v[218:221], v[40:43]
	v_mfma_f32_16x16x32_bf16 v[36:39], v[196:199], v[218:221], v[36:39]
	v_mfma_f32_16x16x32_bf16 v[24:27], v[188:191], v[226:229], v[24:27]
	v_mfma_f32_16x16x32_bf16 v[20:23], v[196:199], v[226:229], v[20:23]
	v_mfma_f32_16x16x32_bf16 v[8:11], v[188:191], v[234:237], v[8:11]
	v_mfma_f32_16x16x32_bf16 v[4:7], v[196:199], v[234:237], v[4:7]
	s_setprio 0
	s_barrier
	s_add_i32 s55, s55, 2
	s_add_u32 s44, s44, 0x100
	s_addc_u32 s45, s45, 0
	s_cmp_gt_u32 s55, 5
	s_cbranch_scc1 .LBB0_469
	s_branch .LBB0_467
